# P4 residual x loads of waves 1-7 issued at the end of P3 (before the store-drain wait and barrier)
# baseline (speedup 1.0000x reference)
.LBB0_803:
	v_readfirstlane_b32 s100, v156
	s_nop 0
	s_cmp_eq_u32 s100, 0
	s_cbranch_scc1 .Lp4x_early_w0
	s_and_b32 s98, s2, 7
	s_lshl_b32 s98, s98, 3
	s_bfe_u32 s99, s2, 0x30003
	s_add_i32 s98, s98, s99
	s_lshr_b32 s99, s2, 6
	s_lshr_b32 s44, s100, 8
	s_lshl_b32 s52, s44, 6
	s_lshl_b32 s5, s98, 8
	s_add_i32 s5, s5, s52
	v_or_b32_e32 v4, s5, v3
	v_ashrrev_i32_e32 v5, 31, v4
	v_lshlrev_b64 v[4:5], 12, v[4:5]
	s_lshl_b32 s8, s99, 8
	s_bfe_u32 s3, s100, 0x20006
	v_lshl_add_u64 v[4:5], s[36:37], 0, v[4:5]
	s_ashr_i32 s9, s8, 31
	v_lshl_add_u64 v[4:5], s[8:9], 2, v[4:5]
	s_lshl_b32 s8, s3, 8
	s_mov_b32 s9, 0
	v_mov_b32_e32 v159, 0
	v_lshl_add_u64 v[4:5], v[4:5], 0, s[8:9]
	v_lshlrev_b32_e32 v6, 2, v191
	v_mov_b32_e32 v7, v159
	v_lshl_add_u64 v[116:117], v[4:5], 0, v[6:7]
	s_mov_b32 s5, 0x10000
	v_add_co_u32_e32 v44, vcc, s5, v116
	s_mov_b32 s5, 0x20000
	s_nop 0
	v_addc_co_u32_e32 v45, vcc, 0, v117, vcc
	s_mov_b64 s[12:13], 0x30000
	v_add_co_u32_e32 v52, vcc, s5, v116
	v_lshl_add_u64 v[36:37], v[116:117], 0, s[12:13]
	s_mov_b64 s[12:13], 0x10080
	v_addc_co_u32_e32 v53, vcc, 0, v117, vcc
	s_mov_b32 s5, 0x30000
	v_lshl_add_u64 v[70:71], v[116:117], 0, s[12:13]
	s_mov_b64 s[12:13], 0x20080
	s_mov_b64 s[10:11], 0x10000
	s_mov_b64 s[8:9], 0x20000
	v_add_co_u32_e32 v68, vcc, s5, v116
	v_lshl_add_u64 v[72:73], v[116:117], 0, s[12:13]
	s_mov_b64 s[12:13], 0x30080
	v_lshl_add_u64 v[20:21], v[116:117], 0, s[10:11]
	v_lshl_add_u64 v[46:47], v[116:117], 0, s[8:9]
	v_addc_co_u32_e32 v69, vcc, 0, v117, vcc
	v_lshl_add_u64 v[74:75], v[116:117], 0, s[12:13]
	s_mov_b64 s[12:13], 0x80000
	s_mov_b32 s5, 0x80000
	global_load_dwordx4 v[4:7], v[116:117], off offset:16 nt
	global_load_dwordx4 v[8:11], v[116:117], off nt
	global_load_dwordx4 v[12:15], v[44:45], off nt
	global_load_dwordx4 v[16:19], v[20:21], off offset:16 nt
	s_nop 0
	global_load_dwordx4 v[20:23], v[68:69], off nt
	global_load_dwordx4 v[24:27], v[36:37], off offset:16 nt
	global_load_dwordx4 v[28:31], v[116:117], off offset:144 nt
	global_load_dwordx4 v[32:35], v[116:117], off offset:128 nt
	s_nop 0
	global_load_dwordx4 v[36:39], v[46:47], off offset:16 nt
	global_load_dwordx4 v[40:43], v[44:45], off offset:128 nt
	s_nop 0
	global_load_dwordx4 v[44:47], v[52:53], off nt
	global_load_dwordx4 v[48:51], v[52:53], off offset:128 nt
	s_nop 0
	global_load_dwordx4 v[52:55], v[70:71], off offset:16 nt
	global_load_dwordx4 v[56:59], v[68:69], off offset:128 nt
	global_load_dwordx4 v[60:63], v[72:73], off offset:16 nt
	global_load_dwordx4 v[64:67], v[74:75], off offset:16 nt
	v_lshl_add_u64 v[72:73], v[116:117], 0, s[12:13]
	v_add_co_u32_e32 v88, vcc, s5, v116
	s_mov_b64 s[12:13], 0x90000
	s_nop 0
	v_addc_co_u32_e32 v89, vcc, 0, v117, vcc
	v_lshl_add_u64 v[84:85], v[116:117], 0, s[12:13]
	s_mov_b32 s5, 0x90000
	s_mov_b64 s[12:13], 0xa0000
	v_add_co_u32_e32 v96, vcc, s5, v116
	v_lshl_add_u64 v[80:81], v[116:117], 0, s[12:13]
	s_mov_b64 s[12:13], 0xb0000
	v_addc_co_u32_e32 v97, vcc, 0, v117, vcc
	s_mov_b32 s5, 0xa0000
	v_lshl_add_u64 v[108:109], v[116:117], 0, s[12:13]
	s_mov_b64 s[12:13], 0x80080
	v_add_co_u32_e32 v112, vcc, s5, v116
	v_lshl_add_u64 v[100:101], v[116:117], 0, s[12:13]
	s_mov_b64 s[12:13], 0x90080
	v_addc_co_u32_e32 v113, vcc, 0, v117, vcc
	s_mov_b32 s5, 0xb0000
	v_lshl_add_u64 v[104:105], v[116:117], 0, s[12:13]
	s_mov_b64 s[12:13], 0xa0080
	v_add_co_u32_e32 v120, vcc, s5, v116
	v_lshl_add_u64 v[124:125], v[116:117], 0, s[12:13]
	s_mov_b64 s[12:13], 0xb0080
	v_addc_co_u32_e32 v121, vcc, 0, v117, vcc
	v_lshl_add_u64 v[128:129], v[116:117], 0, s[12:13]
	global_load_dwordx4 v[68:71], v[88:89], off nt
	s_nop 0
	global_load_dwordx4 v[72:75], v[72:73], off offset:16 nt
	s_nop 0
	global_load_dwordx4 v[76:79], v[112:113], off nt
	s_nop 0
	global_load_dwordx4 v[80:83], v[80:81], off offset:16 nt
	s_nop 0
	global_load_dwordx4 v[84:87], v[84:85], off offset:16 nt
	s_nop 0
	global_load_dwordx4 v[88:91], v[88:89], off offset:128 nt
	s_nop 0
	global_load_dwordx4 v[92:95], v[96:97], off nt
	s_nop 0
	global_load_dwordx4 v[96:99], v[96:97], off offset:128 nt
	s_nop 0
	global_load_dwordx4 v[100:103], v[100:101], off offset:16 nt
	s_nop 0
	global_load_dwordx4 v[104:107], v[104:105], off offset:16 nt
	s_nop 0
	global_load_dwordx4 v[108:111], v[108:109], off offset:16 nt
	s_nop 0
	global_load_dwordx4 v[112:115], v[112:113], off offset:128 nt
	s_nop 0
	global_load_dwordx4 v[116:119], v[120:121], off nt
	s_nop 0
	global_load_dwordx4 v[120:123], v[120:121], off offset:128 nt
	s_nop 0
	global_load_dwordx4 v[124:127], v[124:125], off offset:16 nt
	s_nop 0
	global_load_dwordx4 v[128:131], v[128:129], off offset:16 nt
	s_waitcnt vmcnt(32)
	s_branch .Lp4x_early_join

.Lp4x_early_join:
	s_barrier

.LBB0_907:
	s_and_b64 vcc, exec, s[6:7]
	s_cbranch_vccnz .LBB0_1013
	s_cmp_eq_u32 s100, 0
	s_cbranch_scc1 .Lp4x_arr_w0
	s_waitcnt vmcnt(32)
	s_branch .Lp4x_arr_join

.Lp4x_arr_join:
	v_mov_b32_e32 v134, 1
	v_mov_b32_e32 v1, 0
	v_mov_b32_e32 v132, 1
	s_waitcnt lgkmcnt(0)
	s_barrier
	s_and_saveexec_b64 s[8:9], s[96:97]
	s_cbranch_execz .LBB0_927
	s_mov_b32 s3, 0x27160
	s_addk_i32 s3, 0x100
	v_mov_b32_e32 v1, s3
	s_mov_b32 s3, 0x27164
	s_waitcnt vmcnt(0) expcnt(0) lgkmcnt(0)
	ds_read_b32 v134, v1
	s_addk_i32 s3, 0x100
	v_mov_b32_e32 v1, s3
	ds_read_b32 v132, v1
	s_waitcnt lgkmcnt(1)
	v_cmp_ne_u32_e32 vcc, 0, v134
	s_cbranch_vccnz .LBB0_924
	v_readlane_b32 s12, v254, 18
	v_readlane_b32 s13, v254, 19
	s_mul_i32 s3, s13, s12
	s_lshl_b32 s3, s3, 8
	s_mov_b32 s5, 1
	v_mov_b32_e32 v19, 0
	v_readlane_b32 s14, v254, 20
	v_readlane_b32 s15, v254, 21
	s_branch .LBB0_912

.LBB0_927:
	s_or_b64 exec, exec, s[8:9]
	s_mov_b64 s[98:99], s[36:37]
	s_cmp_eq_u32 s39, 0
	s_cbranch_scc1 .Lp4x_skip_w0
	s_lshr_b32 s44, s39, 8
	s_lshl_b32 s52, s44, 6
	s_bfe_u32 s3, s39, 0x20006
	v_mov_b32_e32 v159, 0
	s_mov_b64 s[10:11], 0x10000
	s_mov_b64 s[8:9], 0x20000
